# stack1 + leading waves prefetch 3 of 4 initial PV V-fragments at softmax start
# speedup vs baseline: 1.0007x; 1.0007x over previous
.LBB0_722:
	s_and_b64 vcc, exec, s[6:7]
	s_cbranch_vccz .Lattn_nohoist
	v_add_u32_e32 v250, s54, v160
	ds_read_b128 v[220:223], v250 offset:50176
	ds_read_b128 v[242:245], v250 offset:51200
	ds_read_b128 v[246:249], v250 offset:52224
.Lattn_nohoist:
	v_max3_f32 v0, v142, s63, v143
	v_max3_f32 v0, v0, v144, v145
	v_max3_f32 v0, v0, v138, v139
	v_max3_f32 v0, v0, v140, v141
	v_max3_f32 v0, v0, v118, v119
	v_max3_f32 v0, v0, v120, v121
	v_max3_f32 v0, v0, v114, v115
	v_max3_f32 v0, v0, v116, v117
	ds_bpermute_b32 v190, v232, v0
	s_andn2_b64 vcc, exec, s[6:7]
	s_waitcnt lgkmcnt(0)
	v_max_f32_e32 v190, v190, v190
	v_max_f32_e32 v0, v0, v190
	ds_bpermute_b32 v190, v233, v0
	s_waitcnt lgkmcnt(0)
	v_max3_f32 v239, v189, v0, v190
	v_sub_f32_e32 v138, v138, v239
	v_exp_f32_e32 v203, v138
	v_sub_f32_e32 v138, v139, v239
	v_exp_f32_e32 v201, v138
	v_sub_f32_e32 v138, v140, v239
	v_sub_f32_e32 v114, v114, v239
	v_exp_f32_e32 v199, v138
	v_sub_f32_e32 v138, v141, v239
	v_exp_f32_e32 v141, v114
	v_sub_f32_e32 v114, v115, v239
	v_exp_f32_e32 v139, v114
	v_sub_f32_e32 v114, v116, v239
	v_sub_f32_e32 v0, v189, v239
	v_sub_f32_e32 v143, v143, v239
	v_exp_f32_e32 v189, v114
	v_sub_f32_e32 v114, v117, v239
	v_exp_f32_e32 v209, v143
	v_exp_f32_e32 v143, v114
	v_max3_f32 v114, v134, s63, v135
	v_max3_f32 v114, v114, v136, v137
	v_max3_f32 v114, v114, v130, v131
	v_sub_f32_e32 v118, v118, v239
	v_max3_f32 v114, v114, v132, v133
	v_exp_f32_e32 v195, v118
	v_sub_f32_e32 v118, v119, v239
	v_max3_f32 v114, v114, v126, v127
	v_exp_f32_e32 v193, v118
	v_sub_f32_e32 v118, v120, v239
	v_max3_f32 v114, v114, v128, v129
	v_sub_f32_e32 v145, v145, v239
	v_exp_f32_e32 v191, v118
	v_sub_f32_e32 v118, v121, v239
	v_max3_f32 v114, v114, v122, v123
	v_exp_f32_e32 v205, v145
	v_exp_f32_e32 v145, v118
	v_max3_f32 v118, v114, v124, v125
	ds_bpermute_b32 v119, v232, v118
	v_exp_f32_e32 v197, v138
	v_sub_f32_e32 v142, v142, v239
	v_exp_f32_e32 v211, v142
	v_sub_f32_e32 v144, v144, v239
	s_waitcnt lgkmcnt(0)
	v_max_f32_e32 v119, v119, v119
	v_max_f32_e32 v138, v118, v119
	ds_bpermute_b32 v140, v233, v138
	v_exp_f32_e32 v0, v0
	v_exp_f32_e32 v207, v144
	v_cvt_pk_bf16_f32 v114, v211, v209
	v_cvt_pk_bf16_f32 v115, v207, v205
	s_waitcnt lgkmcnt(0)
	v_max3_f32 v240, v188, v138, v140
	v_sub_f32_e32 v130, v130, v240
	v_sub_f32_e32 v134, v134, v240
	v_exp_f32_e32 v202, v130
	v_sub_f32_e32 v130, v131, v240
	v_sub_f32_e32 v126, v126, v240
	v_sub_f32_e32 v122, v122, v240
	v_exp_f32_e32 v210, v134
	v_sub_f32_e32 v134, v135, v240
	v_exp_f32_e32 v200, v130
	v_sub_f32_e32 v130, v132, v240
	v_exp_f32_e32 v194, v126
	v_sub_f32_e32 v126, v127, v240
	v_exp_f32_e32 v140, v122
	v_sub_f32_e32 v122, v123, v240
	v_sub_f32_e32 v142, v188, v240
	v_exp_f32_e32 v208, v134
	v_sub_f32_e32 v134, v136, v240
	v_exp_f32_e32 v198, v130
	v_sub_f32_e32 v130, v133, v240
	v_exp_f32_e32 v192, v126
	v_sub_f32_e32 v126, v128, v240
	v_exp_f32_e32 v138, v122
	v_sub_f32_e32 v122, v124, v240
	v_exp_f32_e32 v206, v134
	v_sub_f32_e32 v134, v137, v240
	v_exp_f32_e32 v196, v130
	v_exp_f32_e32 v190, v126
	v_sub_f32_e32 v126, v129, v240
	v_exp_f32_e32 v130, v142
	v_exp_f32_e32 v188, v122
	v_sub_f32_e32 v122, v125, v240
	v_exp_f32_e32 v204, v134
	v_exp_f32_e32 v144, v126
	v_exp_f32_e32 v142, v122
	v_pk_mul_f32 v[112:113], v[112:113], v[0:1] op_sel_hi:[1,0]
	v_pk_mul_f32 v[110:111], v[110:111], v[0:1] op_sel_hi:[1,0]
	v_pk_mul_f32 v[108:109], v[108:109], v[0:1] op_sel_hi:[1,0]
	v_pk_mul_f32 v[106:107], v[106:107], v[0:1] op_sel_hi:[1,0]
	v_pk_mul_f32 v[104:105], v[104:105], v[0:1] op_sel_hi:[1,0]
	v_pk_mul_f32 v[102:103], v[102:103], v[0:1] op_sel_hi:[1,0]
	v_pk_mul_f32 v[100:101], v[100:101], v[0:1] op_sel_hi:[1,0]
	v_pk_mul_f32 v[98:99], v[98:99], v[0:1] op_sel_hi:[1,0]
	v_pk_mul_f32 v[92:93], v[92:93], v[0:1] op_sel_hi:[1,0]
	v_pk_mul_f32 v[90:91], v[90:91], v[0:1] op_sel_hi:[1,0]
	v_pk_mul_f32 v[72:73], v[72:73], v[0:1] op_sel_hi:[1,0]
	v_pk_mul_f32 v[70:71], v[70:71], v[0:1] op_sel_hi:[1,0]
	v_pk_mul_f32 v[40:41], v[40:41], v[0:1] op_sel_hi:[1,0]
	v_pk_mul_f32 v[38:39], v[38:39], v[0:1] op_sel_hi:[1,0]
	v_pk_mul_f32 v[36:37], v[36:37], v[0:1] op_sel_hi:[1,0]
	v_pk_mul_f32 v[34:35], v[34:35], v[0:1] op_sel_hi:[1,0]
	v_pk_mul_f32 v[32:33], v[32:33], v[130:131] op_sel_hi:[1,0]
	v_pk_mul_f32 v[30:31], v[30:31], v[130:131] op_sel_hi:[1,0]
	v_pk_mul_f32 v[28:29], v[28:29], v[130:131] op_sel_hi:[1,0]
	v_pk_mul_f32 v[26:27], v[26:27], v[130:131] op_sel_hi:[1,0]
	v_pk_mul_f32 v[24:25], v[24:25], v[130:131] op_sel_hi:[1,0]
	v_pk_mul_f32 v[22:23], v[22:23], v[130:131] op_sel_hi:[1,0]
	v_pk_mul_f32 v[20:21], v[20:21], v[130:131] op_sel_hi:[1,0]
	v_pk_mul_f32 v[18:19], v[18:19], v[130:131] op_sel_hi:[1,0]
	v_pk_mul_f32 v[16:17], v[16:17], v[130:131] op_sel_hi:[1,0]
	v_pk_mul_f32 v[14:15], v[14:15], v[130:131] op_sel_hi:[1,0]
	v_pk_mul_f32 v[12:13], v[12:13], v[130:131] op_sel_hi:[1,0]
	v_pk_mul_f32 v[10:11], v[10:11], v[130:131] op_sel_hi:[1,0]
	v_pk_mul_f32 v[8:9], v[8:9], v[130:131] op_sel_hi:[1,0]
	v_pk_mul_f32 v[6:7], v[6:7], v[130:131] op_sel_hi:[1,0]
	v_pk_mul_f32 v[4:5], v[4:5], v[130:131] op_sel_hi:[1,0]
	v_pk_mul_f32 v[2:3], v[2:3], v[130:131] op_sel_hi:[1,0]
	v_cvt_pk_bf16_f32 v116, v203, v201
	v_cvt_pk_bf16_f32 v117, v199, v197
	v_cvt_pk_bf16_f32 v118, v195, v193
	v_cvt_pk_bf16_f32 v119, v191, v145
	v_cvt_pk_bf16_f32 v120, v141, v139
	v_cvt_pk_bf16_f32 v121, v189, v143
	v_cvt_pk_bf16_f32 v122, v210, v208
	v_cvt_pk_bf16_f32 v123, v206, v204
	v_cvt_pk_bf16_f32 v124, v202, v200
	v_cvt_pk_bf16_f32 v125, v198, v196
	v_cvt_pk_bf16_f32 v126, v194, v192
	v_cvt_pk_bf16_f32 v127, v190, v144
	v_cvt_pk_bf16_f32 v128, v140, v138
	v_cvt_pk_bf16_f32 v129, v188, v142
	s_cbranch_vccnz .LBB0_727
	v_add_u32_e32 v131, s54, v160
	ds_read_b128 v[132:135], v131 offset:49152
	s_waitcnt lgkmcnt(0)
	v_mfma_f32_16x16x32_bf16 v[110:113], v[132:135], v[114:117], v[110:113]
	v_mfma_f32_16x16x32_bf16 v[30:33], v[132:135], v[122:125], v[30:33]
	s_waitcnt lgkmcnt(2)
	v_mfma_f32_16x16x32_bf16 v[110:113], v[220:223], v[118:121], v[110:113]
	v_mfma_f32_16x16x32_bf16 v[30:33], v[220:223], v[126:129], v[30:33]
	ds_read_b128 v[132:135], v131 offset:53248
	ds_read_b128 v[220:223], v131 offset:54272
	s_waitcnt lgkmcnt(2)
	v_mfma_f32_16x16x32_bf16 v[106:109], v[242:245], v[114:117], v[106:109]
	v_mfma_f32_16x16x32_bf16 v[26:29], v[242:245], v[122:125], v[26:29]
	v_mfma_f32_16x16x32_bf16 v[106:109], v[246:249], v[118:121], v[106:109]
	v_mfma_f32_16x16x32_bf16 v[26:29], v[246:249], v[126:129], v[26:29]
	ds_read_b128 v[242:245], v131 offset:55296
	ds_read_b128 v[246:249], v131 offset:56320
	s_waitcnt lgkmcnt(2)
	v_mfma_f32_16x16x32_bf16 v[102:105], v[132:135], v[114:117], v[102:105]
	v_mfma_f32_16x16x32_bf16 v[22:25], v[132:135], v[122:125], v[22:25]
	v_mfma_f32_16x16x32_bf16 v[102:105], v[220:223], v[118:121], v[102:105]
	v_mfma_f32_16x16x32_bf16 v[22:25], v[220:223], v[126:129], v[22:25]
	ds_read_b128 v[132:135], v131 offset:57344
	ds_read_b128 v[220:223], v131 offset:58368
	s_waitcnt lgkmcnt(2)
	v_mfma_f32_16x16x32_bf16 v[98:101], v[242:245], v[114:117], v[98:101]
	v_mfma_f32_16x16x32_bf16 v[18:21], v[242:245], v[122:125], v[18:21]
	v_mfma_f32_16x16x32_bf16 v[98:101], v[246:249], v[118:121], v[98:101]
	v_mfma_f32_16x16x32_bf16 v[18:21], v[246:249], v[126:129], v[18:21]
	ds_read_b128 v[242:245], v131 offset:59392
	ds_read_b128 v[246:249], v131 offset:60416
	s_waitcnt lgkmcnt(2)
	v_mfma_f32_16x16x32_bf16 v[90:93], v[132:135], v[114:117], v[90:93]
	v_mfma_f32_16x16x32_bf16 v[14:17], v[132:135], v[122:125], v[14:17]
	v_mfma_f32_16x16x32_bf16 v[90:93], v[220:223], v[118:121], v[90:93]
	v_mfma_f32_16x16x32_bf16 v[14:17], v[220:223], v[126:129], v[14:17]
	ds_read_b128 v[132:135], v131 offset:61440
	ds_read_b128 v[220:223], v131 offset:62464
	s_waitcnt lgkmcnt(2)
	v_mfma_f32_16x16x32_bf16 v[70:73], v[242:245], v[114:117], v[70:73]
	v_mfma_f32_16x16x32_bf16 v[10:13], v[242:245], v[122:125], v[10:13]
	v_mfma_f32_16x16x32_bf16 v[70:73], v[246:249], v[118:121], v[70:73]
	v_mfma_f32_16x16x32_bf16 v[10:13], v[246:249], v[126:129], v[10:13]
	ds_read_b128 v[242:245], v131 offset:63488
	ds_read_b128 v[246:249], v131 offset:64512
	s_waitcnt lgkmcnt(2)
	v_mfma_f32_16x16x32_bf16 v[38:41], v[132:135], v[114:117], v[38:41]
	v_mfma_f32_16x16x32_bf16 v[6:9], v[132:135], v[122:125], v[6:9]
	v_mfma_f32_16x16x32_bf16 v[38:41], v[220:223], v[118:121], v[38:41]
	v_mfma_f32_16x16x32_bf16 v[6:9], v[220:223], v[126:129], v[6:9]
	s_waitcnt lgkmcnt(0)
	v_mfma_f32_16x16x32_bf16 v[34:37], v[242:245], v[114:117], v[34:37]
	v_mfma_f32_16x16x32_bf16 v[2:5], v[242:245], v[122:125], v[2:5]
	v_mfma_f32_16x16x32_bf16 v[34:37], v[246:249], v[118:121], v[34:37]
	v_mfma_f32_16x16x32_bf16 v[2:5], v[246:249], v[126:129], v[2:5]
	s_mov_b64 s[4:5], 0
	s_branch .LBB0_728
